# MLP-up, out-proj and MLP-down GEMMs: first two k-phase waits after an epilogue no longer drain the epilogue stores
# baseline (speedup 1.0000x reference)
.LBB0_880:
	s_add_i32 m0, s19, 0x18000
	v_lshl_add_u64 v[8:9], v[8:9], 0, s[62:63]
	s_waitcnt vmcnt(2)
	s_barrier
	global_load_lds_dwordx4 v[8:9], off
	v_lshl_add_u64 v[8:9], v[10:11], 0, s[62:63]
	s_add_i32 m0, s19, 0x1a000
	s_add_i32 s23, s19, 0x8000
	global_load_lds_dwordx4 v[8:9], off
	v_lshl_add_u64 v[8:9], v[12:13], 0, s[62:63]
	s_mov_b32 m0, s23
	s_add_i32 s24, s19, 0xa000
	global_load_lds_dwordx4 v[8:9], off
	v_lshl_add_u64 v[8:9], v[14:15], 0, s[62:63]
	s_mov_b32 m0, s24
	s_lshl_b32 s5, s5, 5
	global_load_lds_dwordx4 v[8:9], off
	v_lshl_add_u64 v[8:9], v[4:5], 0, s[84:85]
	s_add_i32 m0, s19, 0x1c000
	v_lshl_add_u64 v[10:11], v[8:9], 0, v[0:1]
	global_load_lds_dwordx4 v[10:11], off
	v_lshl_add_u64 v[8:9], v[8:9], 0, v[136:137]
	s_add_i32 m0, s19, 0x1e000
	s_and_b32 s5, s5, 0x60
	global_load_lds_dwordx4 v[8:9], off
	v_lshrrev_b32_e32 v9, 1, v16
	v_and_b32_e32 v9, 24, v9
	v_and_b32_e32 v8, 15, v16
	v_lshlrev_b32_e32 v10, 1, v9
	v_lshl_or_b32 v162, s10, 6, v8
	v_lshl_or_b32 v8, v8, 6, v10
	v_lshlrev_b32_e32 v10, 2, v16
	s_lshl_b32 s10, s10, 13
	v_and_b32_e32 v10, 32, v10
	v_bitop3_b32 v11, v8, s10, v10 bitop3:0xde
	s_lshl_b32 s10, s5, 7
	v_bitop3_b32 v163, v8, s10, v10 bitop3:0xde
	v_lshlrev_b32_e32 v8, 14, v17
	v_and_b32_e32 v8, 0xffff8000, v8
	v_or_b32_e32 v164, s5, v9
	v_lshl_add_u32 v8, v18, 11, v8
	v_and_b32_e32 v9, 1, v17
	v_lshl_or_b32 v8, v9, 6, v8
	v_lshl_add_u32 v142, v19, 1, v8
	v_lshlrev_b32_e32 v8, 14, v21
	v_and_b32_e32 v8, 0xffff8000, v8
	s_waitcnt vmcnt(6)
	v_lshl_add_u32 v8, v20, 11, v8
	v_and_b32_e32 v9, 1, v21
	s_cmpk_lt_u32 s4, 0x100
	v_lshl_or_b32 v8, v9, 6, v8
	v_readlane_b32 s4, v254, 47
	s_cselect_b64 s[10:11], -1, 0
	v_mov_b32_e32 v143, v1
	v_lshl_add_u32 v144, v22, 1, v8
	v_mov_b32_e32 v145, v1
	s_mov_b32 s25, 0
	v_add_u32_e32 v165, 0, v11
	v_readlane_b32 s26, v254, 25
	s_mov_b32 s27, s4
	s_barrier
	v_readlane_b32 s5, v254, 48
	s_mov_b32 s98, 0
	s_branch .LBB0_883

.LBB0_882:
	s_mov_b32 s98, 1
	s_andn2_b64 vcc, exec, s[16:17]
	s_mov_b32 s26, s12
	s_mov_b32 s27, s14
	v_mov_b64_e32 v[4:5], v[148:149]
	v_mov_b64_e32 v[6:7], v[146:147]
	s_cbranch_vccz .LBB0_896

.LBB0_890:
	s_cmp_eq_u32 s13, 12
	s_cselect_b64 vcc, -1, 0
	s_add_i32 s15, 0, 0x10000
	s_add_i32 s16, 0, 0x14000
	v_lshl_add_u64 v[158:159], v[156:157], 0, s[88:89]
	v_add_u32_e32 v174, s15, v163
	v_add_u32_e32 v190, s16, v163
	v_cndmask_b32_e32 v195, v159, v151, vcc
	v_cndmask_b32_e32 v194, v158, v150, vcc
	ds_read_b128 v[158:161], v174
	ds_read_b128 v[166:169], v174 offset:1024
	ds_read_b128 v[170:173], v174 offset:2048
	ds_read_b128 v[174:177], v174 offset:3072
	ds_read_b128 v[178:181], v190
	ds_read_b128 v[182:185], v190 offset:1024
	ds_read_b128 v[186:189], v190 offset:2048
	ds_read_b128 v[190:193], v190 offset:3072
	v_cndmask_b32_e32 v197, v155, v153, vcc
	v_cndmask_b32_e32 v196, v154, v152, vcc
	v_lshl_add_u64 v[232:233], v[156:157], 0, v[144:145]
	s_add_i32 m0, s19, 0xc000
	ds_read_b128 v[200:203], v165
	ds_read_b128 v[204:207], v165 offset:1024
	ds_read_b128 v[208:211], v165 offset:2048
	ds_read_b128 v[212:215], v165 offset:3072
	ds_read_b128 v[216:219], v165 offset:4096
	ds_read_b128 v[220:223], v165 offset:5120
	ds_read_b128 v[224:227], v165 offset:6144
	ds_read_b128 v[228:231], v165 offset:7168
	global_load_lds_dwordx4 v[232:233], off
	v_lshl_add_u64 v[232:233], v[156:157], 0, v[142:143]
	s_add_i32 m0, s19, 0xe000
	s_nop 0
	global_load_lds_dwordx4 v[232:233], off
	s_cmp_lg_u32 s98, 0
	s_cbranch_scc1 .Lgr_g7_1
	s_waitcnt vmcnt(8)
.Lgr_g7_1:
	s_waitcnt vmcnt(63)
	s_waitcnt lgkmcnt(0)
	s_barrier
	s_setprio 1
	s_waitcnt lgkmcnt(0)
	v_mfma_f32_16x16x32_bf16 v[128:131], v[158:161], v[200:203], v[128:131]
	v_mfma_f32_16x16x32_bf16 v[124:127], v[170:173], v[200:203], v[124:127]
	v_mfma_f32_16x16x32_bf16 v[120:123], v[158:161], v[208:211], v[120:123]
	v_mfma_f32_16x16x32_bf16 v[116:119], v[170:173], v[208:211], v[116:119]
	v_mfma_f32_16x16x32_bf16 v[108:111], v[158:161], v[216:219], v[108:111]
	v_mfma_f32_16x16x32_bf16 v[100:103], v[170:173], v[216:219], v[100:103]
	v_mfma_f32_16x16x32_bf16 v[92:95], v[158:161], v[224:227], v[92:95]
	v_mfma_f32_16x16x32_bf16 v[84:87], v[170:173], v[224:227], v[84:87]
	v_mfma_f32_16x16x32_bf16 v[128:131], v[166:169], v[204:207], v[128:131]
	v_mfma_f32_16x16x32_bf16 v[124:127], v[174:177], v[204:207], v[124:127]
	v_mfma_f32_16x16x32_bf16 v[120:123], v[166:169], v[212:215], v[120:123]
	v_mfma_f32_16x16x32_bf16 v[116:119], v[174:177], v[212:215], v[116:119]
	v_mfma_f32_16x16x32_bf16 v[108:111], v[166:169], v[220:223], v[108:111]
	v_mfma_f32_16x16x32_bf16 v[100:103], v[174:177], v[220:223], v[100:103]
	v_mfma_f32_16x16x32_bf16 v[92:95], v[166:169], v[228:231], v[92:95]
	v_mfma_f32_16x16x32_bf16 v[84:87], v[174:177], v[228:231], v[84:87]
	s_setprio 0
	s_setprio 1
	v_mfma_f32_16x16x32_bf16 v[112:115], v[178:181], v[200:203], v[112:115]
	v_mfma_f32_16x16x32_bf16 v[104:107], v[186:189], v[200:203], v[104:107]
	v_mfma_f32_16x16x32_bf16 v[96:99], v[178:181], v[208:211], v[96:99]
	v_mfma_f32_16x16x32_bf16 v[88:91], v[186:189], v[208:211], v[88:91]
	v_mfma_f32_16x16x32_bf16 v[80:83], v[178:181], v[216:219], v[80:83]
	v_mfma_f32_16x16x32_bf16 v[76:79], v[186:189], v[216:219], v[76:79]
	v_mfma_f32_16x16x32_bf16 v[72:75], v[178:181], v[224:227], v[72:75]
	v_mfma_f32_16x16x32_bf16 v[68:71], v[186:189], v[224:227], v[68:71]
	v_mfma_f32_16x16x32_bf16 v[112:115], v[182:185], v[204:207], v[112:115]
	v_mfma_f32_16x16x32_bf16 v[104:107], v[190:193], v[204:207], v[104:107]
	v_mfma_f32_16x16x32_bf16 v[96:99], v[182:185], v[212:215], v[96:99]
	v_mfma_f32_16x16x32_bf16 v[88:91], v[190:193], v[212:215], v[88:91]
	v_mfma_f32_16x16x32_bf16 v[80:83], v[182:185], v[220:223], v[80:83]
	v_mfma_f32_16x16x32_bf16 v[76:79], v[190:193], v[220:223], v[76:79]
	v_mfma_f32_16x16x32_bf16 v[72:75], v[182:185], v[228:231], v[72:75]
	v_mfma_f32_16x16x32_bf16 v[68:71], v[190:193], v[228:231], v[68:71]
	s_setprio 0
	s_barrier
	s_add_i32 s15, s15, s18
	v_lshl_add_u64 v[232:233], v[196:197], 0, v[0:1]
	s_mov_b32 m0, s15
	ds_read_b128 v[200:203], v165 offset:16384
	ds_read_b128 v[204:207], v165 offset:17408
	ds_read_b128 v[208:211], v165 offset:18432
	ds_read_b128 v[212:215], v165 offset:19456
	ds_read_b128 v[216:219], v165 offset:20480
	ds_read_b128 v[220:223], v165 offset:21504
	ds_read_b128 v[224:227], v165 offset:22528
	ds_read_b128 v[228:231], v165 offset:23552
	global_load_lds_dwordx4 v[232:233], off
	v_lshl_add_u64 v[234:235], v[196:197], 0, v[136:137]
	s_add_i32 m0, s15, 0x2000
	v_lshl_add_u64 v[236:237], v[196:197], 0, s[64:65]
	s_add_i32 s15, s16, s18
	global_load_lds_dwordx4 v[234:235], off
	v_lshl_add_u64 v[238:239], v[236:237], 0, v[0:1]
	s_mov_b32 m0, s15
	v_lshl_add_u64 v[236:237], v[236:237], 0, v[136:137]
	global_load_lds_dwordx4 v[238:239], off
	s_add_i32 m0, s15, 0x2000
	v_lshl_add_u64 v[238:239], v[194:195], 0, v[138:139]
	global_load_lds_dwordx4 v[236:237], off
	v_lshl_add_u64 v[236:237], v[194:195], 0, v[140:141]
	s_mov_b32 m0, s19
	s_nop 0
	global_load_lds_dwordx4 v[236:237], off
	s_mov_b32 m0, s20
	s_nop 0
	global_load_lds_dwordx4 v[238:239], off
	s_cmp_lg_u32 s98, 0
	s_cbranch_scc1 .Lgr_g7_2
	s_waitcnt vmcnt(8)
.Lgr_g7_2:
	s_waitcnt vmcnt(63)
	s_mov_b32 s98, 0
	s_waitcnt lgkmcnt(0)
	s_barrier
	s_setprio 1
	s_waitcnt lgkmcnt(0)
	v_mfma_f32_16x16x32_bf16 v[64:67], v[158:161], v[200:203], v[64:67]
	v_mfma_f32_16x16x32_bf16 v[60:63], v[170:173], v[200:203], v[60:63]
	v_mfma_f32_16x16x32_bf16 v[56:59], v[158:161], v[208:211], v[56:59]
	v_mfma_f32_16x16x32_bf16 v[48:51], v[170:173], v[208:211], v[48:51]
	v_mfma_f32_16x16x32_bf16 v[40:43], v[158:161], v[216:219], v[40:43]
	v_mfma_f32_16x16x32_bf16 v[32:35], v[170:173], v[216:219], v[32:35]
	v_mfma_f32_16x16x32_bf16 v[24:27], v[158:161], v[224:227], v[24:27]
	v_mfma_f32_16x16x32_bf16 v[16:19], v[170:173], v[224:227], v[16:19]
	v_mfma_f32_16x16x32_bf16 v[64:67], v[166:169], v[204:207], v[64:67]
	v_mfma_f32_16x16x32_bf16 v[60:63], v[174:177], v[204:207], v[60:63]
	v_mfma_f32_16x16x32_bf16 v[56:59], v[166:169], v[212:215], v[56:59]
	v_mfma_f32_16x16x32_bf16 v[48:51], v[174:177], v[212:215], v[48:51]
	v_mfma_f32_16x16x32_bf16 v[40:43], v[166:169], v[220:223], v[40:43]
	v_mfma_f32_16x16x32_bf16 v[32:35], v[174:177], v[220:223], v[32:35]
	v_mfma_f32_16x16x32_bf16 v[24:27], v[166:169], v[228:231], v[24:27]
	v_mfma_f32_16x16x32_bf16 v[16:19], v[174:177], v[228:231], v[16:19]
	s_setprio 0
	s_setprio 1
	v_mfma_f32_16x16x32_bf16 v[52:55], v[178:181], v[200:203], v[52:55]
	v_mfma_f32_16x16x32_bf16 v[44:47], v[186:189], v[200:203], v[44:47]
	v_mfma_f32_16x16x32_bf16 v[36:39], v[178:181], v[208:211], v[36:39]
	v_mfma_f32_16x16x32_bf16 v[28:31], v[186:189], v[208:211], v[28:31]
	v_mfma_f32_16x16x32_bf16 v[20:23], v[178:181], v[216:219], v[20:23]
	v_mfma_f32_16x16x32_bf16 v[12:15], v[186:189], v[216:219], v[12:15]
	v_mfma_f32_16x16x32_bf16 v[8:11], v[178:181], v[224:227], v[8:11]
	v_mfma_f32_16x16x32_bf16 v[4:7], v[186:189], v[224:227], v[4:7]
	v_mfma_f32_16x16x32_bf16 v[52:55], v[182:185], v[204:207], v[52:55]
	v_mfma_f32_16x16x32_bf16 v[44:47], v[190:193], v[204:207], v[44:47]
	v_mfma_f32_16x16x32_bf16 v[36:39], v[182:185], v[212:215], v[36:39]
	v_mfma_f32_16x16x32_bf16 v[28:31], v[190:193], v[212:215], v[28:31]
	v_mfma_f32_16x16x32_bf16 v[20:23], v[182:185], v[220:223], v[20:23]
	v_mfma_f32_16x16x32_bf16 v[12:15], v[190:193], v[220:223], v[12:15]
	v_mfma_f32_16x16x32_bf16 v[8:11], v[182:185], v[228:231], v[8:11]
	v_mfma_f32_16x16x32_bf16 v[4:7], v[190:193], v[228:231], v[4:7]
	s_setprio 0
	s_barrier
	s_add_i32 s15, 0, 0x18000
	s_add_i32 s16, 0, 0x1c000
	v_add_u32_e32 v174, s15, v163
	v_add_u32_e32 v190, s16, v163
	ds_read_b128 v[158:161], v174
	ds_read_b128 v[166:169], v174 offset:1024
	ds_read_b128 v[170:173], v174 offset:2048
	ds_read_b128 v[174:177], v174 offset:3072
	ds_read_b128 v[178:181], v190
	ds_read_b128 v[182:185], v190 offset:1024
	ds_read_b128 v[186:189], v190 offset:2048
	ds_read_b128 v[190:193], v190 offset:3072
	v_lshl_add_u64 v[194:195], v[194:195], 0, s[64:65]
	s_mov_b32 m0, s21
	v_lshl_add_u64 v[240:241], v[194:195], 0, v[140:141]
	ds_read_b128 v[200:203], v165 offset:32768
	ds_read_b128 v[204:207], v165 offset:33792
	ds_read_b128 v[208:211], v165 offset:34816
	ds_read_b128 v[212:215], v165 offset:35840
	ds_read_b128 v[216:219], v165 offset:36864
	ds_read_b128 v[220:223], v165 offset:37888
	ds_read_b128 v[224:227], v165 offset:38912
	ds_read_b128 v[228:231], v165 offset:39936
	global_load_lds_dwordx4 v[240:241], off
	v_lshl_add_u64 v[194:195], v[194:195], 0, v[138:139]
	s_mov_b32 m0, s22
	s_nop 0
	global_load_lds_dwordx4 v[194:195], off
	s_waitcnt vmcnt(8)
	s_waitcnt lgkmcnt(0)
	s_barrier
	s_setprio 1
	s_waitcnt lgkmcnt(0)
	v_mfma_f32_16x16x32_bf16 v[128:131], v[158:161], v[200:203], v[128:131]
	v_mfma_f32_16x16x32_bf16 v[124:127], v[170:173], v[200:203], v[124:127]
	v_mfma_f32_16x16x32_bf16 v[120:123], v[158:161], v[208:211], v[120:123]
	v_mfma_f32_16x16x32_bf16 v[116:119], v[170:173], v[208:211], v[116:119]
	v_mfma_f32_16x16x32_bf16 v[108:111], v[158:161], v[216:219], v[108:111]
	v_mfma_f32_16x16x32_bf16 v[100:103], v[170:173], v[216:219], v[100:103]
	v_mfma_f32_16x16x32_bf16 v[92:95], v[158:161], v[224:227], v[92:95]
	v_mfma_f32_16x16x32_bf16 v[84:87], v[170:173], v[224:227], v[84:87]
	v_mfma_f32_16x16x32_bf16 v[128:131], v[166:169], v[204:207], v[128:131]
	v_mfma_f32_16x16x32_bf16 v[124:127], v[174:177], v[204:207], v[124:127]
	v_mfma_f32_16x16x32_bf16 v[120:123], v[166:169], v[212:215], v[120:123]
	v_mfma_f32_16x16x32_bf16 v[116:119], v[174:177], v[212:215], v[116:119]
	v_mfma_f32_16x16x32_bf16 v[108:111], v[166:169], v[220:223], v[108:111]
	v_mfma_f32_16x16x32_bf16 v[100:103], v[174:177], v[220:223], v[100:103]
	v_mfma_f32_16x16x32_bf16 v[92:95], v[166:169], v[228:231], v[92:95]
	v_mfma_f32_16x16x32_bf16 v[84:87], v[174:177], v[228:231], v[84:87]
	s_setprio 0
	s_setprio 1
	v_mfma_f32_16x16x32_bf16 v[112:115], v[178:181], v[200:203], v[112:115]
	v_mfma_f32_16x16x32_bf16 v[104:107], v[186:189], v[200:203], v[104:107]
	v_mfma_f32_16x16x32_bf16 v[96:99], v[178:181], v[208:211], v[96:99]
	v_mfma_f32_16x16x32_bf16 v[88:91], v[186:189], v[208:211], v[88:91]
	v_mfma_f32_16x16x32_bf16 v[80:83], v[178:181], v[216:219], v[80:83]
	v_mfma_f32_16x16x32_bf16 v[76:79], v[186:189], v[216:219], v[76:79]
	v_mfma_f32_16x16x32_bf16 v[72:75], v[178:181], v[224:227], v[72:75]
	v_mfma_f32_16x16x32_bf16 v[68:71], v[186:189], v[224:227], v[68:71]
	v_mfma_f32_16x16x32_bf16 v[112:115], v[182:185], v[204:207], v[112:115]
	v_mfma_f32_16x16x32_bf16 v[104:107], v[190:193], v[204:207], v[104:107]
	v_mfma_f32_16x16x32_bf16 v[96:99], v[182:185], v[212:215], v[96:99]
	v_mfma_f32_16x16x32_bf16 v[88:91], v[190:193], v[212:215], v[88:91]
	v_mfma_f32_16x16x32_bf16 v[80:83], v[182:185], v[220:223], v[80:83]
	v_mfma_f32_16x16x32_bf16 v[76:79], v[190:193], v[220:223], v[76:79]
	v_mfma_f32_16x16x32_bf16 v[72:75], v[182:185], v[228:231], v[72:75]
	v_mfma_f32_16x16x32_bf16 v[68:71], v[190:193], v[228:231], v[68:71]
	s_setprio 0
	s_barrier
	s_add_i32 s15, s15, s18
	v_lshl_add_u64 v[194:195], v[232:233], 0, s[62:63]
	s_mov_b32 m0, s15
	ds_read_b128 v[200:203], v165 offset:49152
	ds_read_b128 v[204:207], v165 offset:50176
	ds_read_b128 v[208:211], v165 offset:51200
	ds_read_b128 v[212:215], v165 offset:52224
	ds_read_b128 v[216:219], v165 offset:53248
	ds_read_b128 v[220:223], v165 offset:54272
	ds_read_b128 v[224:227], v165 offset:55296
	ds_read_b128 v[228:231], v165 offset:56320
	global_load_lds_dwordx4 v[194:195], off
	v_lshl_add_u64 v[194:195], v[234:235], 0, s[62:63]
	s_add_i32 m0, s15, 0x2000
	s_add_i32 s15, s16, s18
	global_load_lds_dwordx4 v[194:195], off
	v_lshl_add_u64 v[194:195], v[196:197], 0, s[84:85]
	v_lshl_add_u64 v[196:197], v[194:195], 0, v[0:1]
	s_mov_b32 m0, s15
	v_lshl_add_u64 v[194:195], v[194:195], 0, v[136:137]
	global_load_lds_dwordx4 v[196:197], off
	s_add_i32 m0, s15, 0x2000
	s_nop 0
	global_load_lds_dwordx4 v[194:195], off
	v_lshl_add_u64 v[194:195], v[236:237], 0, s[62:63]
	s_mov_b32 m0, s23
	s_nop 0
	global_load_lds_dwordx4 v[194:195], off
	v_lshl_add_u64 v[194:195], v[238:239], 0, s[62:63]
	s_mov_b32 m0, s24
	s_nop 0
	global_load_lds_dwordx4 v[194:195], off
	s_waitcnt vmcnt(8)
	s_waitcnt lgkmcnt(0)
	s_barrier
	s_setprio 1
	s_waitcnt lgkmcnt(0)
	v_mfma_f32_16x16x32_bf16 v[64:67], v[158:161], v[200:203], v[64:67]
	v_mfma_f32_16x16x32_bf16 v[60:63], v[170:173], v[200:203], v[60:63]
	v_mfma_f32_16x16x32_bf16 v[56:59], v[158:161], v[208:211], v[56:59]
	v_mfma_f32_16x16x32_bf16 v[48:51], v[170:173], v[208:211], v[48:51]
	v_mfma_f32_16x16x32_bf16 v[40:43], v[158:161], v[216:219], v[40:43]
	v_mfma_f32_16x16x32_bf16 v[32:35], v[170:173], v[216:219], v[32:35]
	v_mfma_f32_16x16x32_bf16 v[24:27], v[158:161], v[224:227], v[24:27]
	v_mfma_f32_16x16x32_bf16 v[16:19], v[170:173], v[224:227], v[16:19]
	v_mfma_f32_16x16x32_bf16 v[64:67], v[166:169], v[204:207], v[64:67]
	v_mfma_f32_16x16x32_bf16 v[60:63], v[174:177], v[204:207], v[60:63]
	v_mfma_f32_16x16x32_bf16 v[56:59], v[166:169], v[212:215], v[56:59]
	v_mfma_f32_16x16x32_bf16 v[48:51], v[174:177], v[212:215], v[48:51]
	v_mfma_f32_16x16x32_bf16 v[40:43], v[166:169], v[220:223], v[40:43]
	v_mfma_f32_16x16x32_bf16 v[32:35], v[174:177], v[220:223], v[32:35]
	v_mfma_f32_16x16x32_bf16 v[24:27], v[166:169], v[228:231], v[24:27]
	v_mfma_f32_16x16x32_bf16 v[16:19], v[174:177], v[228:231], v[16:19]
	s_setprio 0
	s_setprio 1
	v_mfma_f32_16x16x32_bf16 v[52:55], v[178:181], v[200:203], v[52:55]
	v_mfma_f32_16x16x32_bf16 v[44:47], v[186:189], v[200:203], v[44:47]
	v_mfma_f32_16x16x32_bf16 v[36:39], v[178:181], v[208:211], v[36:39]
	v_mfma_f32_16x16x32_bf16 v[28:31], v[186:189], v[208:211], v[28:31]
	v_mfma_f32_16x16x32_bf16 v[20:23], v[178:181], v[216:219], v[20:23]
	v_mfma_f32_16x16x32_bf16 v[12:15], v[186:189], v[216:219], v[12:15]
	v_mfma_f32_16x16x32_bf16 v[8:11], v[178:181], v[224:227], v[8:11]
	v_mfma_f32_16x16x32_bf16 v[4:7], v[186:189], v[224:227], v[4:7]
	v_mfma_f32_16x16x32_bf16 v[52:55], v[182:185], v[204:207], v[52:55]
	v_mfma_f32_16x16x32_bf16 v[44:47], v[190:193], v[204:207], v[44:47]
	v_mfma_f32_16x16x32_bf16 v[36:39], v[182:185], v[212:215], v[36:39]
	v_mfma_f32_16x16x32_bf16 v[28:31], v[190:193], v[212:215], v[28:31]
	v_mfma_f32_16x16x32_bf16 v[20:23], v[182:185], v[220:223], v[20:23]
	v_mfma_f32_16x16x32_bf16 v[12:15], v[190:193], v[220:223], v[12:15]
	v_mfma_f32_16x16x32_bf16 v[8:11], v[182:185], v[228:231], v[8:11]
	v_mfma_f32_16x16x32_bf16 v[4:7], v[190:193], v[228:231], v[4:7]
	s_setprio 0
	s_barrier
	s_add_i32 s13, s13, 2
	v_lshl_add_u64 v[154:155], v[154:155], 0, s[86:87]
	s_cmp_gt_u32 s13, 13
	v_lshl_add_u64 v[156:157], v[156:157], 0, s[86:87]
	s_cbranch_scc0 .LBB0_890
	s_and_b64 vcc, exec, s[10:11]
	s_cbranch_vccz .LBB0_893
	s_barrier

.LBB0_997:
	s_add_i32 m0, s19, 0x18000
	v_lshl_add_u64 v[8:9], v[8:9], 0, s[62:63]
	s_waitcnt vmcnt(2)
	s_barrier
	global_load_lds_dwordx4 v[8:9], off
	v_lshl_add_u64 v[8:9], v[10:11], 0, s[62:63]
	s_add_i32 m0, s19, 0x1a000
	s_add_i32 s23, s19, 0x8000
	global_load_lds_dwordx4 v[8:9], off
	v_lshl_add_u64 v[8:9], v[12:13], 0, s[62:63]
	s_mov_b32 m0, s23
	s_add_i32 s24, s19, 0xa000
	global_load_lds_dwordx4 v[8:9], off
	v_lshl_add_u64 v[8:9], v[14:15], 0, s[62:63]
	s_mov_b32 m0, s24
	s_mov_b64 s[12:13], 0x8b89000
	global_load_lds_dwordx4 v[8:9], off
	v_lshl_add_u64 v[8:9], v[2:3], 0, s[84:85]
	s_add_i32 m0, s19, 0x1c000
	v_lshl_add_u64 v[10:11], v[8:9], 0, v[0:1]
	global_load_lds_dwordx4 v[10:11], off
	v_lshl_add_u64 v[8:9], v[8:9], 0, v[134:135]
	s_add_i32 m0, s19, 0x1e000
	v_lshl_add_u64 v[140:141], v[6:7], 0, s[12:13]
	global_load_lds_dwordx4 v[8:9], off
	v_lshrrev_b32_e32 v7, 1, v16
	v_and_b32_e32 v7, 24, v7
	v_and_b32_e32 v6, 15, v16
	v_lshlrev_b32_e32 v8, 1, v7
	v_lshl_or_b32 v158, s10, 6, v6
	v_lshl_or_b32 v6, v6, 6, v8
	v_lshlrev_b32_e32 v8, 2, v16
	s_lshl_b32 s5, s5, 5
	s_lshl_b32 s10, s10, 13
	v_and_b32_e32 v8, 32, v8
	s_and_b32 s5, s5, 0x60
	v_bitop3_b32 v9, v6, s10, v8 bitop3:0xde
	s_lshl_b32 s10, s5, 7
	v_bitop3_b32 v159, v6, s10, v8 bitop3:0xde
	v_lshlrev_b32_e32 v6, 14, v17
	v_and_b32_e32 v6, 0xffff8000, v6
	v_or_b32_e32 v160, s5, v7
	v_lshl_add_u32 v6, v18, 11, v6
	v_and_b32_e32 v7, 1, v17
	v_lshl_or_b32 v6, v7, 6, v6
	v_lshl_add_u32 v142, v19, 1, v6
	v_lshlrev_b32_e32 v6, 14, v21
	v_and_b32_e32 v6, 0xffff8000, v6
	s_waitcnt vmcnt(6)
	v_lshl_add_u32 v6, v20, 11, v6
	v_and_b32_e32 v7, 1, v21
	s_cmpk_lt_u32 s4, 0x100
	v_lshl_or_b32 v6, v7, 6, v6
	v_readlane_b32 s4, v254, 31
	s_cselect_b64 s[10:11], -1, 0
	v_mov_b32_e32 v143, v1
	v_lshl_add_u32 v144, v22, 1, v6
	v_mov_b32_e32 v145, v1
	s_mov_b32 s25, 0
	v_add_u32_e32 v161, 0, v9
	v_readlane_b32 s26, v254, 30
	s_mov_b32 s27, s4
	s_mov_b32 s31, 0x100000
	s_barrier
	v_readlane_b32 s5, v254, 32
	s_mov_b32 s98, 0
	s_branch .LBB0_1000

.LBB0_999:
	s_mov_b32 s98, 1
	s_andn2_b64 vcc, exec, s[4:5]
	s_mov_b32 s26, s12
	s_mov_b32 s27, s14
	v_mov_b64_e32 v[2:3], v[148:149]
	v_mov_b64_e32 v[4:5], v[146:147]
	s_cbranch_vccz .LBB0_1013

.LBB0_1007:
	s_cmp_eq_u32 s13, 12
	s_cselect_b64 vcc, -1, 0
	s_add_i32 s15, 0, 0x10000
	s_add_i32 s16, 0, 0x14000
	v_lshl_add_u64 v[162:163], v[156:157], 0, s[88:89]
	v_add_u32_e32 v174, s15, v159
	v_add_u32_e32 v190, s16, v159
	v_cndmask_b32_e32 v195, v163, v151, vcc
	v_cndmask_b32_e32 v194, v162, v150, vcc
	ds_read_b128 v[162:165], v174
	ds_read_b128 v[166:169], v174 offset:1024
	ds_read_b128 v[170:173], v174 offset:2048
	ds_read_b128 v[174:177], v174 offset:3072
	ds_read_b128 v[178:181], v190
	ds_read_b128 v[182:185], v190 offset:1024
	ds_read_b128 v[186:189], v190 offset:2048
	ds_read_b128 v[190:193], v190 offset:3072
	v_cndmask_b32_e32 v197, v155, v153, vcc
	v_cndmask_b32_e32 v196, v154, v152, vcc
	v_lshl_add_u64 v[232:233], v[156:157], 0, v[144:145]
	s_add_i32 m0, s19, 0xc000
	ds_read_b128 v[200:203], v161
	ds_read_b128 v[204:207], v161 offset:1024
	ds_read_b128 v[208:211], v161 offset:2048
	ds_read_b128 v[212:215], v161 offset:3072
	ds_read_b128 v[216:219], v161 offset:4096
	ds_read_b128 v[220:223], v161 offset:5120
	ds_read_b128 v[224:227], v161 offset:6144
	ds_read_b128 v[228:231], v161 offset:7168
	global_load_lds_dwordx4 v[232:233], off
	v_lshl_add_u64 v[232:233], v[156:157], 0, v[142:143]
	s_add_i32 m0, s19, 0xe000
	s_nop 0
	global_load_lds_dwordx4 v[232:233], off
	s_cmp_lg_u32 s98, 0
	s_cbranch_scc1 .Lgr_g9_1
	s_waitcnt vmcnt(8)
.Lgr_g9_1:
	s_waitcnt vmcnt(24)
	s_waitcnt lgkmcnt(0)
	s_barrier
	s_setprio 1
	s_waitcnt lgkmcnt(0)
	v_mfma_f32_16x16x32_bf16 v[126:129], v[162:165], v[200:203], v[126:129]
	v_mfma_f32_16x16x32_bf16 v[122:125], v[170:173], v[200:203], v[122:125]
	v_mfma_f32_16x16x32_bf16 v[110:113], v[162:165], v[208:211], v[110:113]
	v_mfma_f32_16x16x32_bf16 v[106:109], v[170:173], v[208:211], v[106:109]
	v_mfma_f32_16x16x32_bf16 v[94:97], v[162:165], v[216:219], v[94:97]
	v_mfma_f32_16x16x32_bf16 v[90:93], v[170:173], v[216:219], v[90:93]
	v_mfma_f32_16x16x32_bf16 v[78:81], v[162:165], v[224:227], v[78:81]
	v_mfma_f32_16x16x32_bf16 v[74:77], v[170:173], v[224:227], v[74:77]
	v_mfma_f32_16x16x32_bf16 v[126:129], v[166:169], v[204:207], v[126:129]
	v_mfma_f32_16x16x32_bf16 v[122:125], v[174:177], v[204:207], v[122:125]
	v_mfma_f32_16x16x32_bf16 v[110:113], v[166:169], v[212:215], v[110:113]
	v_mfma_f32_16x16x32_bf16 v[106:109], v[174:177], v[212:215], v[106:109]
	v_mfma_f32_16x16x32_bf16 v[94:97], v[166:169], v[220:223], v[94:97]
	v_mfma_f32_16x16x32_bf16 v[90:93], v[174:177], v[220:223], v[90:93]
	v_mfma_f32_16x16x32_bf16 v[78:81], v[166:169], v[228:231], v[78:81]
	v_mfma_f32_16x16x32_bf16 v[74:77], v[174:177], v[228:231], v[74:77]
	s_setprio 0
	s_setprio 1
	v_mfma_f32_16x16x32_bf16 v[118:121], v[178:181], v[200:203], v[118:121]
	v_mfma_f32_16x16x32_bf16 v[114:117], v[186:189], v[200:203], v[114:117]
	v_mfma_f32_16x16x32_bf16 v[102:105], v[178:181], v[208:211], v[102:105]
	v_mfma_f32_16x16x32_bf16 v[98:101], v[186:189], v[208:211], v[98:101]
	v_mfma_f32_16x16x32_bf16 v[86:89], v[178:181], v[216:219], v[86:89]
	v_mfma_f32_16x16x32_bf16 v[82:85], v[186:189], v[216:219], v[82:85]
	v_mfma_f32_16x16x32_bf16 v[70:73], v[178:181], v[224:227], v[70:73]
	v_mfma_f32_16x16x32_bf16 v[66:69], v[186:189], v[224:227], v[66:69]
	v_mfma_f32_16x16x32_bf16 v[118:121], v[182:185], v[204:207], v[118:121]
	v_mfma_f32_16x16x32_bf16 v[114:117], v[190:193], v[204:207], v[114:117]
	v_mfma_f32_16x16x32_bf16 v[102:105], v[182:185], v[212:215], v[102:105]
	v_mfma_f32_16x16x32_bf16 v[98:101], v[190:193], v[212:215], v[98:101]
	v_mfma_f32_16x16x32_bf16 v[86:89], v[182:185], v[220:223], v[86:89]
	v_mfma_f32_16x16x32_bf16 v[82:85], v[190:193], v[220:223], v[82:85]
	v_mfma_f32_16x16x32_bf16 v[70:73], v[182:185], v[228:231], v[70:73]
	v_mfma_f32_16x16x32_bf16 v[66:69], v[190:193], v[228:231], v[66:69]
	s_setprio 0
	s_barrier
	s_add_i32 s15, s15, s18
	v_lshl_add_u64 v[232:233], v[196:197], 0, v[0:1]
	s_mov_b32 m0, s15
	ds_read_b128 v[200:203], v161 offset:16384
	ds_read_b128 v[204:207], v161 offset:17408
	ds_read_b128 v[208:211], v161 offset:18432
	ds_read_b128 v[212:215], v161 offset:19456
	ds_read_b128 v[216:219], v161 offset:20480
	ds_read_b128 v[220:223], v161 offset:21504
	ds_read_b128 v[224:227], v161 offset:22528
	ds_read_b128 v[228:231], v161 offset:23552
	global_load_lds_dwordx4 v[232:233], off
	v_lshl_add_u64 v[234:235], v[196:197], 0, v[134:135]
	s_add_i32 m0, s15, 0x2000
	v_lshl_add_u64 v[236:237], v[196:197], 0, s[64:65]
	s_add_i32 s15, s16, s18
	global_load_lds_dwordx4 v[234:235], off
	v_lshl_add_u64 v[238:239], v[236:237], 0, v[0:1]
	s_mov_b32 m0, s15
	v_lshl_add_u64 v[236:237], v[236:237], 0, v[134:135]
	global_load_lds_dwordx4 v[238:239], off
	s_add_i32 m0, s15, 0x2000
	v_lshl_add_u64 v[238:239], v[194:195], 0, v[136:137]
	global_load_lds_dwordx4 v[236:237], off
	v_lshl_add_u64 v[236:237], v[194:195], 0, v[138:139]
	s_mov_b32 m0, s19
	s_nop 0
	global_load_lds_dwordx4 v[236:237], off
	s_mov_b32 m0, s20
	s_nop 0
	global_load_lds_dwordx4 v[238:239], off
	s_cmp_lg_u32 s98, 0
	s_cbranch_scc1 .Lgr_g9_2
	s_waitcnt vmcnt(8)
.Lgr_g9_2:
	s_waitcnt vmcnt(24)
	s_mov_b32 s98, 0
	s_waitcnt lgkmcnt(0)
	s_barrier
	s_setprio 1
	s_waitcnt lgkmcnt(0)
	v_mfma_f32_16x16x32_bf16 v[62:65], v[162:165], v[200:203], v[62:65]
	v_mfma_f32_16x16x32_bf16 v[58:61], v[170:173], v[200:203], v[58:61]
	v_mfma_f32_16x16x32_bf16 v[46:49], v[162:165], v[208:211], v[46:49]
	v_mfma_f32_16x16x32_bf16 v[42:45], v[170:173], v[208:211], v[42:45]
	v_mfma_f32_16x16x32_bf16 v[30:33], v[162:165], v[216:219], v[30:33]
	v_mfma_f32_16x16x32_bf16 v[26:29], v[170:173], v[216:219], v[26:29]
	v_mfma_f32_16x16x32_bf16 v[14:17], v[162:165], v[224:227], v[14:17]
	v_mfma_f32_16x16x32_bf16 v[10:13], v[170:173], v[224:227], v[10:13]
	v_mfma_f32_16x16x32_bf16 v[62:65], v[166:169], v[204:207], v[62:65]
	v_mfma_f32_16x16x32_bf16 v[58:61], v[174:177], v[204:207], v[58:61]
	v_mfma_f32_16x16x32_bf16 v[46:49], v[166:169], v[212:215], v[46:49]
	v_mfma_f32_16x16x32_bf16 v[42:45], v[174:177], v[212:215], v[42:45]
	v_mfma_f32_16x16x32_bf16 v[30:33], v[166:169], v[220:223], v[30:33]
	v_mfma_f32_16x16x32_bf16 v[26:29], v[174:177], v[220:223], v[26:29]
	v_mfma_f32_16x16x32_bf16 v[14:17], v[166:169], v[228:231], v[14:17]
	v_mfma_f32_16x16x32_bf16 v[10:13], v[174:177], v[228:231], v[10:13]
	s_setprio 0
	s_setprio 1
	v_mfma_f32_16x16x32_bf16 v[54:57], v[178:181], v[200:203], v[54:57]
	v_mfma_f32_16x16x32_bf16 v[50:53], v[186:189], v[200:203], v[50:53]
	v_mfma_f32_16x16x32_bf16 v[38:41], v[178:181], v[208:211], v[38:41]
	v_mfma_f32_16x16x32_bf16 v[34:37], v[186:189], v[208:211], v[34:37]
	v_mfma_f32_16x16x32_bf16 v[22:25], v[178:181], v[216:219], v[22:25]
	v_mfma_f32_16x16x32_bf16 v[18:21], v[186:189], v[216:219], v[18:21]
	v_mfma_f32_16x16x32_bf16 v[6:9], v[178:181], v[224:227], v[6:9]
	v_mfma_f32_16x16x32_bf16 v[2:5], v[186:189], v[224:227], v[2:5]
	v_mfma_f32_16x16x32_bf16 v[54:57], v[182:185], v[204:207], v[54:57]
	v_mfma_f32_16x16x32_bf16 v[50:53], v[190:193], v[204:207], v[50:53]
	v_mfma_f32_16x16x32_bf16 v[38:41], v[182:185], v[212:215], v[38:41]
	v_mfma_f32_16x16x32_bf16 v[34:37], v[190:193], v[212:215], v[34:37]
	v_mfma_f32_16x16x32_bf16 v[22:25], v[182:185], v[220:223], v[22:25]
	v_mfma_f32_16x16x32_bf16 v[18:21], v[190:193], v[220:223], v[18:21]
	v_mfma_f32_16x16x32_bf16 v[6:9], v[182:185], v[228:231], v[6:9]
	v_mfma_f32_16x16x32_bf16 v[2:5], v[190:193], v[228:231], v[2:5]
	s_setprio 0
	s_barrier
	s_add_i32 s15, 0, 0x18000
	s_add_i32 s16, 0, 0x1c000
	v_add_u32_e32 v174, s15, v159
	v_add_u32_e32 v190, s16, v159
	ds_read_b128 v[162:165], v174
	ds_read_b128 v[166:169], v174 offset:1024
	ds_read_b128 v[170:173], v174 offset:2048
	ds_read_b128 v[174:177], v174 offset:3072
	ds_read_b128 v[178:181], v190
	ds_read_b128 v[182:185], v190 offset:1024
	ds_read_b128 v[186:189], v190 offset:2048
	ds_read_b128 v[190:193], v190 offset:3072
	v_lshl_add_u64 v[194:195], v[194:195], 0, s[64:65]
	s_mov_b32 m0, s21
	v_lshl_add_u64 v[240:241], v[194:195], 0, v[138:139]
	ds_read_b128 v[200:203], v161 offset:32768
	ds_read_b128 v[204:207], v161 offset:33792
	ds_read_b128 v[208:211], v161 offset:34816
	ds_read_b128 v[212:215], v161 offset:35840
	ds_read_b128 v[216:219], v161 offset:36864
	ds_read_b128 v[220:223], v161 offset:37888
	ds_read_b128 v[224:227], v161 offset:38912
	ds_read_b128 v[228:231], v161 offset:39936
	global_load_lds_dwordx4 v[240:241], off
	v_lshl_add_u64 v[194:195], v[194:195], 0, v[136:137]
	s_mov_b32 m0, s22
	s_nop 0
	global_load_lds_dwordx4 v[194:195], off
	s_waitcnt vmcnt(8)
	s_waitcnt lgkmcnt(0)
	s_barrier
	s_setprio 1
	s_waitcnt lgkmcnt(0)
	v_mfma_f32_16x16x32_bf16 v[126:129], v[162:165], v[200:203], v[126:129]
	v_mfma_f32_16x16x32_bf16 v[122:125], v[170:173], v[200:203], v[122:125]
	v_mfma_f32_16x16x32_bf16 v[110:113], v[162:165], v[208:211], v[110:113]
	v_mfma_f32_16x16x32_bf16 v[106:109], v[170:173], v[208:211], v[106:109]
	v_mfma_f32_16x16x32_bf16 v[94:97], v[162:165], v[216:219], v[94:97]
	v_mfma_f32_16x16x32_bf16 v[90:93], v[170:173], v[216:219], v[90:93]
	v_mfma_f32_16x16x32_bf16 v[78:81], v[162:165], v[224:227], v[78:81]
	v_mfma_f32_16x16x32_bf16 v[74:77], v[170:173], v[224:227], v[74:77]
	v_mfma_f32_16x16x32_bf16 v[126:129], v[166:169], v[204:207], v[126:129]
	v_mfma_f32_16x16x32_bf16 v[122:125], v[174:177], v[204:207], v[122:125]
	v_mfma_f32_16x16x32_bf16 v[110:113], v[166:169], v[212:215], v[110:113]
	v_mfma_f32_16x16x32_bf16 v[106:109], v[174:177], v[212:215], v[106:109]
	v_mfma_f32_16x16x32_bf16 v[94:97], v[166:169], v[220:223], v[94:97]
	v_mfma_f32_16x16x32_bf16 v[90:93], v[174:177], v[220:223], v[90:93]
	v_mfma_f32_16x16x32_bf16 v[78:81], v[166:169], v[228:231], v[78:81]
	v_mfma_f32_16x16x32_bf16 v[74:77], v[174:177], v[228:231], v[74:77]
	s_setprio 0
	s_setprio 1
	v_mfma_f32_16x16x32_bf16 v[118:121], v[178:181], v[200:203], v[118:121]
	v_mfma_f32_16x16x32_bf16 v[114:117], v[186:189], v[200:203], v[114:117]
	v_mfma_f32_16x16x32_bf16 v[102:105], v[178:181], v[208:211], v[102:105]
	v_mfma_f32_16x16x32_bf16 v[98:101], v[186:189], v[208:211], v[98:101]
	v_mfma_f32_16x16x32_bf16 v[86:89], v[178:181], v[216:219], v[86:89]
	v_mfma_f32_16x16x32_bf16 v[82:85], v[186:189], v[216:219], v[82:85]
	v_mfma_f32_16x16x32_bf16 v[70:73], v[178:181], v[224:227], v[70:73]
	v_mfma_f32_16x16x32_bf16 v[66:69], v[186:189], v[224:227], v[66:69]
	v_mfma_f32_16x16x32_bf16 v[118:121], v[182:185], v[204:207], v[118:121]
	v_mfma_f32_16x16x32_bf16 v[114:117], v[190:193], v[204:207], v[114:117]
	v_mfma_f32_16x16x32_bf16 v[102:105], v[182:185], v[212:215], v[102:105]
	v_mfma_f32_16x16x32_bf16 v[98:101], v[190:193], v[212:215], v[98:101]
	v_mfma_f32_16x16x32_bf16 v[86:89], v[182:185], v[220:223], v[86:89]
	v_mfma_f32_16x16x32_bf16 v[82:85], v[190:193], v[220:223], v[82:85]
	v_mfma_f32_16x16x32_bf16 v[70:73], v[182:185], v[228:231], v[70:73]
	v_mfma_f32_16x16x32_bf16 v[66:69], v[190:193], v[228:231], v[66:69]
	s_setprio 0
	s_barrier
	s_add_i32 s15, s15, s18
	v_lshl_add_u64 v[194:195], v[232:233], 0, s[62:63]
	s_mov_b32 m0, s15
	ds_read_b128 v[200:203], v161 offset:49152
	ds_read_b128 v[204:207], v161 offset:50176
	ds_read_b128 v[208:211], v161 offset:51200
	ds_read_b128 v[212:215], v161 offset:52224
	ds_read_b128 v[216:219], v161 offset:53248
	ds_read_b128 v[220:223], v161 offset:54272
	ds_read_b128 v[224:227], v161 offset:55296
	ds_read_b128 v[228:231], v161 offset:56320
	global_load_lds_dwordx4 v[194:195], off
	v_lshl_add_u64 v[194:195], v[234:235], 0, s[62:63]
	s_add_i32 m0, s15, 0x2000
	s_add_i32 s15, s16, s18
	global_load_lds_dwordx4 v[194:195], off
	v_lshl_add_u64 v[194:195], v[196:197], 0, s[84:85]
	v_lshl_add_u64 v[196:197], v[194:195], 0, v[0:1]
	s_mov_b32 m0, s15
	v_lshl_add_u64 v[194:195], v[194:195], 0, v[134:135]
	global_load_lds_dwordx4 v[196:197], off
	s_add_i32 m0, s15, 0x2000
	s_nop 0
	global_load_lds_dwordx4 v[194:195], off
	v_lshl_add_u64 v[194:195], v[236:237], 0, s[62:63]
	s_mov_b32 m0, s23
	s_nop 0
	global_load_lds_dwordx4 v[194:195], off
	v_lshl_add_u64 v[194:195], v[238:239], 0, s[62:63]
	s_mov_b32 m0, s24
	s_nop 0
	global_load_lds_dwordx4 v[194:195], off
	s_waitcnt vmcnt(8)
	s_waitcnt lgkmcnt(0)
	s_barrier
	s_setprio 1
	s_waitcnt lgkmcnt(0)
	v_mfma_f32_16x16x32_bf16 v[62:65], v[162:165], v[200:203], v[62:65]
	v_mfma_f32_16x16x32_bf16 v[58:61], v[170:173], v[200:203], v[58:61]
	v_mfma_f32_16x16x32_bf16 v[46:49], v[162:165], v[208:211], v[46:49]
	v_mfma_f32_16x16x32_bf16 v[42:45], v[170:173], v[208:211], v[42:45]
	v_mfma_f32_16x16x32_bf16 v[30:33], v[162:165], v[216:219], v[30:33]
	v_mfma_f32_16x16x32_bf16 v[26:29], v[170:173], v[216:219], v[26:29]
	v_mfma_f32_16x16x32_bf16 v[14:17], v[162:165], v[224:227], v[14:17]
	v_mfma_f32_16x16x32_bf16 v[10:13], v[170:173], v[224:227], v[10:13]
	v_mfma_f32_16x16x32_bf16 v[62:65], v[166:169], v[204:207], v[62:65]
	v_mfma_f32_16x16x32_bf16 v[58:61], v[174:177], v[204:207], v[58:61]
	v_mfma_f32_16x16x32_bf16 v[46:49], v[166:169], v[212:215], v[46:49]
	v_mfma_f32_16x16x32_bf16 v[42:45], v[174:177], v[212:215], v[42:45]
	v_mfma_f32_16x16x32_bf16 v[30:33], v[166:169], v[220:223], v[30:33]
	v_mfma_f32_16x16x32_bf16 v[26:29], v[174:177], v[220:223], v[26:29]
	v_mfma_f32_16x16x32_bf16 v[14:17], v[166:169], v[228:231], v[14:17]
	v_mfma_f32_16x16x32_bf16 v[10:13], v[174:177], v[228:231], v[10:13]
	s_setprio 0
	s_setprio 1
	v_mfma_f32_16x16x32_bf16 v[54:57], v[178:181], v[200:203], v[54:57]
	v_mfma_f32_16x16x32_bf16 v[50:53], v[186:189], v[200:203], v[50:53]
	v_mfma_f32_16x16x32_bf16 v[38:41], v[178:181], v[208:211], v[38:41]
	v_mfma_f32_16x16x32_bf16 v[34:37], v[186:189], v[208:211], v[34:37]
	v_mfma_f32_16x16x32_bf16 v[22:25], v[178:181], v[216:219], v[22:25]
	v_mfma_f32_16x16x32_bf16 v[18:21], v[186:189], v[216:219], v[18:21]
	v_mfma_f32_16x16x32_bf16 v[6:9], v[178:181], v[224:227], v[6:9]
	v_mfma_f32_16x16x32_bf16 v[2:5], v[186:189], v[224:227], v[2:5]
	v_mfma_f32_16x16x32_bf16 v[54:57], v[182:185], v[204:207], v[54:57]
	v_mfma_f32_16x16x32_bf16 v[50:53], v[190:193], v[204:207], v[50:53]
	v_mfma_f32_16x16x32_bf16 v[38:41], v[182:185], v[212:215], v[38:41]
	v_mfma_f32_16x16x32_bf16 v[34:37], v[190:193], v[212:215], v[34:37]
	v_mfma_f32_16x16x32_bf16 v[22:25], v[182:185], v[220:223], v[22:25]
	v_mfma_f32_16x16x32_bf16 v[18:21], v[190:193], v[220:223], v[18:21]
	v_mfma_f32_16x16x32_bf16 v[6:9], v[182:185], v[228:231], v[6:9]
	v_mfma_f32_16x16x32_bf16 v[2:5], v[190:193], v[228:231], v[2:5]
	s_setprio 0
	s_barrier
	s_add_i32 s13, s13, 2
	v_lshl_add_u64 v[154:155], v[154:155], 0, s[86:87]
	s_cmp_gt_u32 s13, 13
	v_lshl_add_u64 v[156:157], v[156:157], 0, s[86:87]
	s_cbranch_scc0 .LBB0_1007
	s_and_b64 vcc, exec, s[10:11]
	s_cbranch_vccz .LBB0_1010
	s_barrier

.LBB0_1064:
	s_add_i32 m0, s17, 0x18000
	v_lshl_add_u64 v[8:9], v[8:9], 0, s[62:63]
	s_waitcnt vmcnt(2)
	s_barrier
	global_load_lds_dwordx4 v[8:9], off
	v_lshl_add_u64 v[8:9], v[10:11], 0, s[62:63]
	s_add_i32 m0, s17, 0x1a000
	s_add_i32 s21, s17, 0x8000
	global_load_lds_dwordx4 v[8:9], off
	v_lshl_add_u64 v[8:9], v[12:13], 0, s[62:63]
	s_mov_b32 m0, s21
	s_add_i32 s22, s17, 0xa000
	global_load_lds_dwordx4 v[8:9], off
	v_lshl_add_u64 v[8:9], v[14:15], 0, s[62:63]
	s_mov_b32 m0, s22
	s_lshl_b32 s5, s5, 5
	global_load_lds_dwordx4 v[8:9], off
	v_lshl_add_u64 v[8:9], v[4:5], 0, s[70:71]
	s_add_i32 m0, s17, 0x1c000
	v_lshl_add_u64 v[10:11], v[8:9], 0, v[0:1]
	global_load_lds_dwordx4 v[10:11], off
	v_lshl_add_u64 v[8:9], v[8:9], 0, v[136:137]
	s_add_i32 m0, s17, 0x1e000
	s_and_b32 s5, s5, 0x60
	global_load_lds_dwordx4 v[8:9], off
	v_lshrrev_b32_e32 v9, 1, v16
	v_and_b32_e32 v9, 24, v9
	v_and_b32_e32 v8, 15, v16
	v_lshlrev_b32_e32 v10, 1, v9
	v_lshl_or_b32 v162, s8, 6, v8
	v_lshl_or_b32 v8, v8, 6, v10
	v_lshlrev_b32_e32 v10, 2, v16
	s_lshl_b32 s8, s8, 13
	v_and_b32_e32 v10, 32, v10
	v_bitop3_b32 v11, v8, s8, v10 bitop3:0xde
	s_lshl_b32 s8, s5, 7
	v_bitop3_b32 v163, v8, s8, v10 bitop3:0xde
	v_lshlrev_b32_e32 v8, 16, v17
	v_and_b32_e32 v8, 0xfffe0000, v8
	v_or_b32_e32 v164, s5, v9
	v_lshl_add_u32 v8, v18, 13, v8
	v_and_b32_e32 v9, 1, v17
	v_lshl_or_b32 v8, v9, 6, v8
	v_lshl_add_u32 v142, v19, 1, v8
	v_lshlrev_b32_e32 v8, 16, v21
	v_and_b32_e32 v8, 0xfffe0000, v8
	s_waitcnt vmcnt(6)
	v_lshl_add_u32 v8, v20, 13, v8
	v_and_b32_e32 v9, 1, v21
	s_cmpk_lt_u32 s4, 0x100
	v_lshl_or_b32 v8, v9, 6, v8
	v_readlane_b32 s4, v254, 47
	s_cselect_b64 s[8:9], -1, 0
	v_mov_b32_e32 v143, v1
	v_lshl_add_u32 v144, v22, 1, v8
	v_mov_b32_e32 v145, v1
	s_mov_b32 s23, 0
	v_add_u32_e32 v165, 0, v11
	v_readlane_b32 s24, v254, 25
	s_mov_b32 s25, s4
	s_barrier
	v_readlane_b32 s5, v254, 48
	s_mov_b32 s98, 0
	s_branch .LBB0_1067

.LBB0_1066:
	s_mov_b32 s98, 1
	s_andn2_b64 vcc, exec, s[14:15]
	s_mov_b32 s24, s10
	s_mov_b32 s25, s12
	v_mov_b64_e32 v[4:5], v[148:149]
	v_mov_b64_e32 v[6:7], v[146:147]
	s_cbranch_vccz .LBB0_1080

.LBB0_1074:
	s_mov_b32 s14, 0xfff00080
	s_cmp_eq_u32 s11, 60
	s_mov_b32 s15, -1
	v_lshl_add_u64 v[194:195], v[156:157], 0, s[14:15]
	s_cselect_b64 vcc, -1, 0
	s_add_i32 s13, 0, 0x10000
	s_add_i32 s14, 0, 0x14000
	v_add_u32_e32 v174, s13, v163
	v_add_u32_e32 v190, s14, v163
	ds_read_b128 v[158:161], v174
	ds_read_b128 v[166:169], v174 offset:1024
	ds_read_b128 v[170:173], v174 offset:2048
	ds_read_b128 v[174:177], v174 offset:3072
	ds_read_b128 v[178:181], v190
	ds_read_b128 v[182:185], v190 offset:1024
	ds_read_b128 v[186:189], v190 offset:2048
	ds_read_b128 v[190:193], v190 offset:3072
	v_cndmask_b32_e32 v195, v195, v151, vcc
	v_cndmask_b32_e32 v194, v194, v150, vcc
	v_cndmask_b32_e32 v197, v155, v153, vcc
	v_cndmask_b32_e32 v196, v154, v152, vcc
	v_lshl_add_u64 v[232:233], v[156:157], 0, v[144:145]
	s_add_i32 m0, s17, 0xc000
	ds_read_b128 v[200:203], v165
	ds_read_b128 v[204:207], v165 offset:1024
	ds_read_b128 v[208:211], v165 offset:2048
	ds_read_b128 v[212:215], v165 offset:3072
	ds_read_b128 v[216:219], v165 offset:4096
	ds_read_b128 v[220:223], v165 offset:5120
	ds_read_b128 v[224:227], v165 offset:6144
	ds_read_b128 v[228:231], v165 offset:7168
	global_load_lds_dwordx4 v[232:233], off
	v_lshl_add_u64 v[232:233], v[156:157], 0, v[142:143]
	s_add_i32 m0, s17, 0xe000
	s_nop 0
	global_load_lds_dwordx4 v[232:233], off
	s_cmp_lg_u32 s98, 0
	s_cbranch_scc1 .Lgr_g10_1
	s_waitcnt vmcnt(8)
.Lgr_g10_1:
	s_waitcnt vmcnt(63)
	s_waitcnt lgkmcnt(0)
	s_barrier
	s_setprio 1
	s_waitcnt lgkmcnt(0)
	v_mfma_f32_16x16x32_bf16 v[128:131], v[158:161], v[200:203], v[128:131]
	v_mfma_f32_16x16x32_bf16 v[124:127], v[170:173], v[200:203], v[124:127]
	v_mfma_f32_16x16x32_bf16 v[120:123], v[158:161], v[208:211], v[120:123]
	v_mfma_f32_16x16x32_bf16 v[116:119], v[170:173], v[208:211], v[116:119]
	v_mfma_f32_16x16x32_bf16 v[108:111], v[158:161], v[216:219], v[108:111]
	v_mfma_f32_16x16x32_bf16 v[100:103], v[170:173], v[216:219], v[100:103]
	v_mfma_f32_16x16x32_bf16 v[92:95], v[158:161], v[224:227], v[92:95]
	v_mfma_f32_16x16x32_bf16 v[84:87], v[170:173], v[224:227], v[84:87]
	v_mfma_f32_16x16x32_bf16 v[128:131], v[166:169], v[204:207], v[128:131]
	v_mfma_f32_16x16x32_bf16 v[124:127], v[174:177], v[204:207], v[124:127]
	v_mfma_f32_16x16x32_bf16 v[120:123], v[166:169], v[212:215], v[120:123]
	v_mfma_f32_16x16x32_bf16 v[116:119], v[174:177], v[212:215], v[116:119]
	v_mfma_f32_16x16x32_bf16 v[108:111], v[166:169], v[220:223], v[108:111]
	v_mfma_f32_16x16x32_bf16 v[100:103], v[174:177], v[220:223], v[100:103]
	v_mfma_f32_16x16x32_bf16 v[92:95], v[166:169], v[228:231], v[92:95]
	v_mfma_f32_16x16x32_bf16 v[84:87], v[174:177], v[228:231], v[84:87]
	s_setprio 0
	s_setprio 1
	v_mfma_f32_16x16x32_bf16 v[112:115], v[178:181], v[200:203], v[112:115]
	v_mfma_f32_16x16x32_bf16 v[104:107], v[186:189], v[200:203], v[104:107]
	v_mfma_f32_16x16x32_bf16 v[96:99], v[178:181], v[208:211], v[96:99]
	v_mfma_f32_16x16x32_bf16 v[88:91], v[186:189], v[208:211], v[88:91]
	v_mfma_f32_16x16x32_bf16 v[80:83], v[178:181], v[216:219], v[80:83]
	v_mfma_f32_16x16x32_bf16 v[76:79], v[186:189], v[216:219], v[76:79]
	v_mfma_f32_16x16x32_bf16 v[72:75], v[178:181], v[224:227], v[72:75]
	v_mfma_f32_16x16x32_bf16 v[68:71], v[186:189], v[224:227], v[68:71]
	v_mfma_f32_16x16x32_bf16 v[112:115], v[182:185], v[204:207], v[112:115]
	v_mfma_f32_16x16x32_bf16 v[104:107], v[190:193], v[204:207], v[104:107]
	v_mfma_f32_16x16x32_bf16 v[96:99], v[182:185], v[212:215], v[96:99]
	v_mfma_f32_16x16x32_bf16 v[88:91], v[190:193], v[212:215], v[88:91]
	v_mfma_f32_16x16x32_bf16 v[80:83], v[182:185], v[220:223], v[80:83]
	v_mfma_f32_16x16x32_bf16 v[76:79], v[190:193], v[220:223], v[76:79]
	v_mfma_f32_16x16x32_bf16 v[72:75], v[182:185], v[228:231], v[72:75]
	v_mfma_f32_16x16x32_bf16 v[68:71], v[190:193], v[228:231], v[68:71]
	s_setprio 0
	s_barrier
	s_add_i32 s13, s13, s16
	v_lshl_add_u64 v[232:233], v[196:197], 0, v[0:1]
	s_mov_b32 m0, s13
	ds_read_b128 v[200:203], v165 offset:16384
	ds_read_b128 v[204:207], v165 offset:17408
	ds_read_b128 v[208:211], v165 offset:18432
	ds_read_b128 v[212:215], v165 offset:19456
	ds_read_b128 v[216:219], v165 offset:20480
	ds_read_b128 v[220:223], v165 offset:21504
	ds_read_b128 v[224:227], v165 offset:22528
	ds_read_b128 v[228:231], v165 offset:23552
	global_load_lds_dwordx4 v[232:233], off
	v_lshl_add_u64 v[234:235], v[196:197], 0, v[136:137]
	s_add_i32 m0, s13, 0x2000
	v_lshl_add_u64 v[236:237], v[196:197], 0, s[72:73]
	s_add_i32 s13, s14, s16
	global_load_lds_dwordx4 v[234:235], off
	v_lshl_add_u64 v[238:239], v[236:237], 0, v[0:1]
	s_mov_b32 m0, s13
	v_lshl_add_u64 v[236:237], v[236:237], 0, v[136:137]
	global_load_lds_dwordx4 v[238:239], off
	s_add_i32 m0, s13, 0x2000
	v_lshl_add_u64 v[238:239], v[194:195], 0, v[138:139]
	global_load_lds_dwordx4 v[236:237], off
	v_lshl_add_u64 v[236:237], v[194:195], 0, v[140:141]
	s_mov_b32 m0, s17
	s_nop 0
	global_load_lds_dwordx4 v[236:237], off
	s_mov_b32 m0, s18
	s_nop 0
	global_load_lds_dwordx4 v[238:239], off
	s_cmp_lg_u32 s98, 0
	s_cbranch_scc1 .Lgr_g10_2
	s_waitcnt vmcnt(8)
.Lgr_g10_2:
	s_waitcnt vmcnt(63)
	s_mov_b32 s98, 0
	s_waitcnt lgkmcnt(0)
	s_barrier
	s_setprio 1
	s_waitcnt lgkmcnt(0)
	v_mfma_f32_16x16x32_bf16 v[64:67], v[158:161], v[200:203], v[64:67]
	v_mfma_f32_16x16x32_bf16 v[60:63], v[170:173], v[200:203], v[60:63]
	v_mfma_f32_16x16x32_bf16 v[56:59], v[158:161], v[208:211], v[56:59]
	v_mfma_f32_16x16x32_bf16 v[48:51], v[170:173], v[208:211], v[48:51]
	v_mfma_f32_16x16x32_bf16 v[40:43], v[158:161], v[216:219], v[40:43]
	v_mfma_f32_16x16x32_bf16 v[32:35], v[170:173], v[216:219], v[32:35]
	v_mfma_f32_16x16x32_bf16 v[24:27], v[158:161], v[224:227], v[24:27]
	v_mfma_f32_16x16x32_bf16 v[16:19], v[170:173], v[224:227], v[16:19]
	v_mfma_f32_16x16x32_bf16 v[64:67], v[166:169], v[204:207], v[64:67]
	v_mfma_f32_16x16x32_bf16 v[60:63], v[174:177], v[204:207], v[60:63]
	v_mfma_f32_16x16x32_bf16 v[56:59], v[166:169], v[212:215], v[56:59]
	v_mfma_f32_16x16x32_bf16 v[48:51], v[174:177], v[212:215], v[48:51]
	v_mfma_f32_16x16x32_bf16 v[40:43], v[166:169], v[220:223], v[40:43]
	v_mfma_f32_16x16x32_bf16 v[32:35], v[174:177], v[220:223], v[32:35]
	v_mfma_f32_16x16x32_bf16 v[24:27], v[166:169], v[228:231], v[24:27]
	v_mfma_f32_16x16x32_bf16 v[16:19], v[174:177], v[228:231], v[16:19]
	s_setprio 0
	s_setprio 1
	v_mfma_f32_16x16x32_bf16 v[52:55], v[178:181], v[200:203], v[52:55]
	v_mfma_f32_16x16x32_bf16 v[44:47], v[186:189], v[200:203], v[44:47]
	v_mfma_f32_16x16x32_bf16 v[36:39], v[178:181], v[208:211], v[36:39]
	v_mfma_f32_16x16x32_bf16 v[28:31], v[186:189], v[208:211], v[28:31]
	v_mfma_f32_16x16x32_bf16 v[20:23], v[178:181], v[216:219], v[20:23]
	v_mfma_f32_16x16x32_bf16 v[12:15], v[186:189], v[216:219], v[12:15]
	v_mfma_f32_16x16x32_bf16 v[8:11], v[178:181], v[224:227], v[8:11]
	v_mfma_f32_16x16x32_bf16 v[4:7], v[186:189], v[224:227], v[4:7]
	v_mfma_f32_16x16x32_bf16 v[52:55], v[182:185], v[204:207], v[52:55]
	v_mfma_f32_16x16x32_bf16 v[44:47], v[190:193], v[204:207], v[44:47]
	v_mfma_f32_16x16x32_bf16 v[36:39], v[182:185], v[212:215], v[36:39]
	v_mfma_f32_16x16x32_bf16 v[28:31], v[190:193], v[212:215], v[28:31]
	v_mfma_f32_16x16x32_bf16 v[20:23], v[182:185], v[220:223], v[20:23]
	v_mfma_f32_16x16x32_bf16 v[12:15], v[190:193], v[220:223], v[12:15]
	v_mfma_f32_16x16x32_bf16 v[8:11], v[182:185], v[228:231], v[8:11]
	v_mfma_f32_16x16x32_bf16 v[4:7], v[190:193], v[228:231], v[4:7]
	s_setprio 0
	s_barrier
	s_add_i32 s13, 0, 0x18000
	s_add_i32 s14, 0, 0x1c000
	v_add_u32_e32 v174, s13, v163
	v_add_u32_e32 v190, s14, v163
	ds_read_b128 v[158:161], v174
	ds_read_b128 v[166:169], v174 offset:1024
	ds_read_b128 v[170:173], v174 offset:2048
	ds_read_b128 v[174:177], v174 offset:3072
	ds_read_b128 v[178:181], v190
	ds_read_b128 v[182:185], v190 offset:1024
	ds_read_b128 v[186:189], v190 offset:2048
	ds_read_b128 v[190:193], v190 offset:3072
	v_lshl_add_u64 v[194:195], v[194:195], 0, s[72:73]
	s_mov_b32 m0, s19
	v_lshl_add_u64 v[240:241], v[194:195], 0, v[140:141]
	ds_read_b128 v[200:203], v165 offset:32768
	ds_read_b128 v[204:207], v165 offset:33792
	ds_read_b128 v[208:211], v165 offset:34816
	ds_read_b128 v[212:215], v165 offset:35840
	ds_read_b128 v[216:219], v165 offset:36864
	ds_read_b128 v[220:223], v165 offset:37888
	ds_read_b128 v[224:227], v165 offset:38912
	ds_read_b128 v[228:231], v165 offset:39936
	global_load_lds_dwordx4 v[240:241], off
	v_lshl_add_u64 v[194:195], v[194:195], 0, v[138:139]
	s_mov_b32 m0, s20
	s_nop 0
	global_load_lds_dwordx4 v[194:195], off
	s_waitcnt vmcnt(8)
	s_waitcnt lgkmcnt(0)
	s_barrier
	s_setprio 1
	s_waitcnt lgkmcnt(0)
	v_mfma_f32_16x16x32_bf16 v[128:131], v[158:161], v[200:203], v[128:131]
	v_mfma_f32_16x16x32_bf16 v[124:127], v[170:173], v[200:203], v[124:127]
	v_mfma_f32_16x16x32_bf16 v[120:123], v[158:161], v[208:211], v[120:123]
	v_mfma_f32_16x16x32_bf16 v[116:119], v[170:173], v[208:211], v[116:119]
	v_mfma_f32_16x16x32_bf16 v[108:111], v[158:161], v[216:219], v[108:111]
	v_mfma_f32_16x16x32_bf16 v[100:103], v[170:173], v[216:219], v[100:103]
	v_mfma_f32_16x16x32_bf16 v[92:95], v[158:161], v[224:227], v[92:95]
	v_mfma_f32_16x16x32_bf16 v[84:87], v[170:173], v[224:227], v[84:87]
	v_mfma_f32_16x16x32_bf16 v[128:131], v[166:169], v[204:207], v[128:131]
	v_mfma_f32_16x16x32_bf16 v[124:127], v[174:177], v[204:207], v[124:127]
	v_mfma_f32_16x16x32_bf16 v[120:123], v[166:169], v[212:215], v[120:123]
	v_mfma_f32_16x16x32_bf16 v[116:119], v[174:177], v[212:215], v[116:119]
	v_mfma_f32_16x16x32_bf16 v[108:111], v[166:169], v[220:223], v[108:111]
	v_mfma_f32_16x16x32_bf16 v[100:103], v[174:177], v[220:223], v[100:103]
	v_mfma_f32_16x16x32_bf16 v[92:95], v[166:169], v[228:231], v[92:95]
	v_mfma_f32_16x16x32_bf16 v[84:87], v[174:177], v[228:231], v[84:87]
	s_setprio 0
	s_setprio 1
	v_mfma_f32_16x16x32_bf16 v[112:115], v[178:181], v[200:203], v[112:115]
	v_mfma_f32_16x16x32_bf16 v[104:107], v[186:189], v[200:203], v[104:107]
	v_mfma_f32_16x16x32_bf16 v[96:99], v[178:181], v[208:211], v[96:99]
	v_mfma_f32_16x16x32_bf16 v[88:91], v[186:189], v[208:211], v[88:91]
	v_mfma_f32_16x16x32_bf16 v[80:83], v[178:181], v[216:219], v[80:83]
	v_mfma_f32_16x16x32_bf16 v[76:79], v[186:189], v[216:219], v[76:79]
	v_mfma_f32_16x16x32_bf16 v[72:75], v[178:181], v[224:227], v[72:75]
	v_mfma_f32_16x16x32_bf16 v[68:71], v[186:189], v[224:227], v[68:71]
	v_mfma_f32_16x16x32_bf16 v[112:115], v[182:185], v[204:207], v[112:115]
	v_mfma_f32_16x16x32_bf16 v[104:107], v[190:193], v[204:207], v[104:107]
	v_mfma_f32_16x16x32_bf16 v[96:99], v[182:185], v[212:215], v[96:99]
	v_mfma_f32_16x16x32_bf16 v[88:91], v[190:193], v[212:215], v[88:91]
	v_mfma_f32_16x16x32_bf16 v[80:83], v[182:185], v[220:223], v[80:83]
	v_mfma_f32_16x16x32_bf16 v[76:79], v[190:193], v[220:223], v[76:79]
	v_mfma_f32_16x16x32_bf16 v[72:75], v[182:185], v[228:231], v[72:75]
	v_mfma_f32_16x16x32_bf16 v[68:71], v[190:193], v[228:231], v[68:71]
	s_setprio 0
	s_barrier
	s_add_i32 s13, s13, s16
	v_lshl_add_u64 v[194:195], v[232:233], 0, s[62:63]
	s_mov_b32 m0, s13
	ds_read_b128 v[200:203], v165 offset:49152
	ds_read_b128 v[204:207], v165 offset:50176
	ds_read_b128 v[208:211], v165 offset:51200
	ds_read_b128 v[212:215], v165 offset:52224
	ds_read_b128 v[216:219], v165 offset:53248
	ds_read_b128 v[220:223], v165 offset:54272
	ds_read_b128 v[224:227], v165 offset:55296
	ds_read_b128 v[228:231], v165 offset:56320
	global_load_lds_dwordx4 v[194:195], off
	v_lshl_add_u64 v[194:195], v[234:235], 0, s[62:63]
	s_add_i32 m0, s13, 0x2000
	s_add_i32 s13, s14, s16
	global_load_lds_dwordx4 v[194:195], off
	v_lshl_add_u64 v[194:195], v[196:197], 0, s[70:71]
	v_lshl_add_u64 v[196:197], v[194:195], 0, v[0:1]
	s_mov_b32 m0, s13
	v_lshl_add_u64 v[194:195], v[194:195], 0, v[136:137]
	global_load_lds_dwordx4 v[196:197], off
	s_add_i32 m0, s13, 0x2000
	s_nop 0
	global_load_lds_dwordx4 v[194:195], off
	v_lshl_add_u64 v[194:195], v[236:237], 0, s[62:63]
	s_mov_b32 m0, s21
	s_nop 0
	global_load_lds_dwordx4 v[194:195], off
	v_lshl_add_u64 v[194:195], v[238:239], 0, s[62:63]
	s_mov_b32 m0, s22
	s_nop 0
	global_load_lds_dwordx4 v[194:195], off
	s_waitcnt vmcnt(8)
	s_waitcnt lgkmcnt(0)
	s_barrier
	s_setprio 1
	s_waitcnt lgkmcnt(0)
	v_mfma_f32_16x16x32_bf16 v[64:67], v[158:161], v[200:203], v[64:67]
	v_mfma_f32_16x16x32_bf16 v[60:63], v[170:173], v[200:203], v[60:63]
	v_mfma_f32_16x16x32_bf16 v[56:59], v[158:161], v[208:211], v[56:59]
	v_mfma_f32_16x16x32_bf16 v[48:51], v[170:173], v[208:211], v[48:51]
	v_mfma_f32_16x16x32_bf16 v[40:43], v[158:161], v[216:219], v[40:43]
	v_mfma_f32_16x16x32_bf16 v[32:35], v[170:173], v[216:219], v[32:35]
	v_mfma_f32_16x16x32_bf16 v[24:27], v[158:161], v[224:227], v[24:27]
	v_mfma_f32_16x16x32_bf16 v[16:19], v[170:173], v[224:227], v[16:19]
	v_mfma_f32_16x16x32_bf16 v[64:67], v[166:169], v[204:207], v[64:67]
	v_mfma_f32_16x16x32_bf16 v[60:63], v[174:177], v[204:207], v[60:63]
	v_mfma_f32_16x16x32_bf16 v[56:59], v[166:169], v[212:215], v[56:59]
	v_mfma_f32_16x16x32_bf16 v[48:51], v[174:177], v[212:215], v[48:51]
	v_mfma_f32_16x16x32_bf16 v[40:43], v[166:169], v[220:223], v[40:43]
	v_mfma_f32_16x16x32_bf16 v[32:35], v[174:177], v[220:223], v[32:35]
	v_mfma_f32_16x16x32_bf16 v[24:27], v[166:169], v[228:231], v[24:27]
	v_mfma_f32_16x16x32_bf16 v[16:19], v[174:177], v[228:231], v[16:19]
	s_setprio 0
	s_setprio 1
	v_mfma_f32_16x16x32_bf16 v[52:55], v[178:181], v[200:203], v[52:55]
	v_mfma_f32_16x16x32_bf16 v[44:47], v[186:189], v[200:203], v[44:47]
	v_mfma_f32_16x16x32_bf16 v[36:39], v[178:181], v[208:211], v[36:39]
	v_mfma_f32_16x16x32_bf16 v[28:31], v[186:189], v[208:211], v[28:31]
	v_mfma_f32_16x16x32_bf16 v[20:23], v[178:181], v[216:219], v[20:23]
	v_mfma_f32_16x16x32_bf16 v[12:15], v[186:189], v[216:219], v[12:15]
	v_mfma_f32_16x16x32_bf16 v[8:11], v[178:181], v[224:227], v[8:11]
	v_mfma_f32_16x16x32_bf16 v[4:7], v[186:189], v[224:227], v[4:7]
	v_mfma_f32_16x16x32_bf16 v[52:55], v[182:185], v[204:207], v[52:55]
	v_mfma_f32_16x16x32_bf16 v[44:47], v[190:193], v[204:207], v[44:47]
	v_mfma_f32_16x16x32_bf16 v[36:39], v[182:185], v[212:215], v[36:39]
	v_mfma_f32_16x16x32_bf16 v[28:31], v[190:193], v[212:215], v[28:31]
	v_mfma_f32_16x16x32_bf16 v[20:23], v[182:185], v[220:223], v[20:23]
	v_mfma_f32_16x16x32_bf16 v[12:15], v[190:193], v[220:223], v[12:15]
	v_mfma_f32_16x16x32_bf16 v[8:11], v[182:185], v[228:231], v[8:11]
	v_mfma_f32_16x16x32_bf16 v[4:7], v[190:193], v[228:231], v[4:7]
	s_setprio 0
	s_barrier
	s_add_i32 s11, s11, 2
	v_lshl_add_u64 v[154:155], v[154:155], 0, s[86:87]
	s_cmp_gt_u32 s11, 61
	v_lshl_add_u64 v[156:157], v[156:157], 0, s[86:87]
	s_cbranch_scc0 .LBB0_1074
	s_and_b64 vcc, exec, s[8:9]
	s_cbranch_vccz .LBB0_1077
	s_barrier
